# adds DPP (quad_perm / row_half_mirror / row_mirror) for the first four steps of the RMSNorm wave reduction instead of ds_bpermute
# baseline (speedup 1.0000x reference)
; DI unsigned pk2(float lo, float hi) { f32x2_t v = {lo, hi}; bf16x2_t b = __builtin_convertvector(v, bf16x2_t); return __builtin_bit_cast(unsigned, b); }
; DI float sx(float v, int mask, int lane) { return __int_as_float(__builtin_amdgcn_ds_bpermute((lane ^ mask) << 2, __float_as_int(v))); }
; DI float wave_sum(float v, int lane) {
; #pragma unroll
;     for (int o = 1; o < 64; o <<= 1) v += sx(v, o, lane);
;     return v;
; }
; DI void phase_norm(const float* xin, const float* g, const float* shift, const float* scale, bf16* hout) {
;     ...
;         for (int j = 0; j < 4; ++j) { v[j] = xr[64 * j]; ss += (v[j].x * v[j].x + v[j].y * v[j].y) + (v[j].z * v[j].z + v[j].w * v[j].w); }
;         const float r = rsqrtf(wave_sum(ss, lane) * (1.f / DM) + EPS);
; #pragma unroll
;         for (int j = 0; j < 4; ++j) { const int col = 4 * lane + 256 * j;
;             const f32x4 gg = *(const f32x4*)(g + col), sc = *(const f32x4*)(scale + b * 6144 + col), sh = *(const f32x4*)(shift + b * 6144 + col);
;             const f32x4 y = (v[j] * r) * gg * (sc + 1.f) + sh;
;             u32x2 w; w.x = pk2(y.x, y.y); w.y = pk2(y.z, y.w);
;             *(u32x2*)(hout + (size_t)row * DM + col) = w; }
.Lnorm_a_body:
	v_mov_b32_e32 v60, v76
	v_mov_b32_e32 v61, v77
	v_mov_b32_e32 v62, v78
	v_mov_b32_e32 v63, v79
	v_mov_b32_e32 v64, v80
	v_mov_b32_e32 v65, v81
	v_mov_b32_e32 v66, v82
	v_mov_b32_e32 v67, v83
	v_mov_b32_e32 v68, v84
	v_mov_b32_e32 v69, v85
	v_mov_b32_e32 v70, v86
	v_mov_b32_e32 v71, v87
	v_mov_b32_e32 v72, v88
	v_mov_b32_e32 v73, v89
	v_mov_b32_e32 v74, v90
	v_mov_b32_e32 v75, v91
	v_ashrrev_i32_e32 v140, 11, v0
	v_mul_i32_i24_e32 v140, 0x1800, v140
	v_ashrrev_i32_e32 v141, 31, v140
	v_lshlrev_b64 v[140:141], 2, v[140:141]
	v_lshl_add_u64 v[150:151], v[4:5], 0, v[140:141]
	v_lshl_add_u64 v[152:153], v[6:7], 0, v[140:141]
	global_load_dwordx4 v[92:95], v[2:3], off
	global_load_dwordx4 v[96:99], v[2:3], off offset:1024
	global_load_dwordx4 v[100:103], v[2:3], off offset:2048
	global_load_dwordx4 v[104:107], v[2:3], off offset:3072
	global_load_dwordx4 v[108:111], v[150:151], off
	global_load_dwordx4 v[112:115], v[150:151], off offset:1024
	global_load_dwordx4 v[116:119], v[150:151], off offset:2048
	global_load_dwordx4 v[120:123], v[150:151], off offset:3072
	global_load_dwordx4 v[124:127], v[152:153], off
	global_load_dwordx4 v[128:131], v[152:153], off offset:1024
	global_load_dwordx4 v[132:135], v[152:153], off offset:2048
	global_load_dwordx4 v[136:139], v[152:153], off offset:3072
	v_add_u32_e32 v146, s84, v0
	v_lshl_add_u64 v[148:149], v[10:11], 0, s[14:15]
	v_cmp_lt_i32_e32 vcc, s56, v146
	s_nop 1
	v_cndmask_b32_e32 v148, v148, v10, vcc
	v_cndmask_b32_e32 v149, v149, v11, vcc
	global_load_dwordx4 v[76:79], v[148:149], off offset:-3072
	global_load_dwordx4 v[80:83], v[148:149], off offset:-2048
	global_load_dwordx4 v[84:87], v[148:149], off offset:-1024
	global_load_dwordx4 v[88:91], v[148:149], off
	v_mul_f32_e32 v154, v60, v60
	v_fmac_f32_e32 v154, v61, v61
	v_mul_f32_e32 v155, v62, v62
	v_fmac_f32_e32 v155, v63, v63
	v_add_f32_e32 v154, v154, v155
	v_mov_b32_e32 v142, v154
	v_mul_f32_e32 v154, v64, v64
	v_fmac_f32_e32 v154, v65, v65
	v_mul_f32_e32 v155, v66, v66
	v_fmac_f32_e32 v155, v67, v67
	v_add_f32_e32 v154, v154, v155
	v_add_f32_e32 v142, v142, v154
	v_mul_f32_e32 v154, v68, v68
	v_fmac_f32_e32 v154, v69, v69
	v_mul_f32_e32 v155, v70, v70
	v_fmac_f32_e32 v155, v71, v71
	v_add_f32_e32 v154, v154, v155
	v_add_f32_e32 v142, v142, v154
	v_mul_f32_e32 v154, v72, v72
	v_fmac_f32_e32 v154, v73, v73
	v_mul_f32_e32 v155, v74, v74
	v_fmac_f32_e32 v155, v75, v75
	v_add_f32_e32 v154, v154, v155
	v_add_f32_e32 v142, v142, v154
	s_nop 1
	v_add_f32_dpp v142, v142, v142 quad_perm:[1,0,3,2] row_mask:0xf bank_mask:0xf
	s_nop 1
	v_add_f32_dpp v142, v142, v142 quad_perm:[2,3,0,1] row_mask:0xf bank_mask:0xf
	s_nop 1
	v_add_f32_dpp v142, v142, v142 row_half_mirror row_mask:0xf bank_mask:0xf
	s_nop 1
	v_add_f32_dpp v142, v142, v142 row_mirror row_mask:0xf bank_mask:0xf
	ds_bpermute_b32 v154, v16, v142
	s_waitcnt lgkmcnt(0)
	v_add_f32_e32 v142, v142, v154
	ds_bpermute_b32 v154, v17, v142
	s_waitcnt lgkmcnt(0)
	v_add_f32_e32 v142, v142, v154
	v_fmamk_f32 v142, v142, 0x3a800000, v198
	v_mul_f32_e32 v154, 0x4b800000, v142
	v_cmp_gt_f32_e32 vcc, s67, v142
	s_nop 1
	v_cndmask_b32_e32 v142, v142, v154, vcc
	v_rsq_f32_e32 v142, v142
	s_nop 0
	v_mul_f32_e32 v154, 0x45800000, v142
	v_cndmask_b32_e32 v144, v142, v154, vcc
	s_waitcnt vmcnt(4)
	v_pk_mul_f32 v[60:61], v[60:61], v[144:145] op_sel_hi:[1,0]
	v_pk_mul_f32 v[62:63], v[62:63], v[144:145] op_sel_hi:[1,0]
	v_pk_mul_f32 v[60:61], v[92:93], v[60:61]
	v_pk_mul_f32 v[62:63], v[94:95], v[62:63]
	v_pk_add_f32 v[108:109], v[108:109], 1.0 op_sel_hi:[1,0]
	v_pk_add_f32 v[110:111], v[110:111], 1.0 op_sel_hi:[1,0]
	v_pk_fma_f32 v[60:61], v[108:109], v[60:61], v[124:125]
	v_pk_fma_f32 v[62:63], v[110:111], v[62:63], v[126:127]
	v_cvt_pk_bf16_f32 v60, v60, v61
	v_cvt_pk_bf16_f32 v61, v62, v63
	global_store_dwordx2 v[8:9], v[60:61], off
	v_pk_mul_f32 v[64:65], v[64:65], v[144:145] op_sel_hi:[1,0]
	v_pk_mul_f32 v[66:67], v[66:67], v[144:145] op_sel_hi:[1,0]
	v_pk_mul_f32 v[64:65], v[96:97], v[64:65]
	v_pk_mul_f32 v[66:67], v[98:99], v[66:67]
	v_pk_add_f32 v[112:113], v[112:113], 1.0 op_sel_hi:[1,0]
	v_pk_add_f32 v[114:115], v[114:115], 1.0 op_sel_hi:[1,0]
	v_pk_fma_f32 v[64:65], v[112:113], v[64:65], v[128:129]
	v_pk_fma_f32 v[66:67], v[114:115], v[66:67], v[130:131]
	v_cvt_pk_bf16_f32 v64, v64, v65
	v_cvt_pk_bf16_f32 v65, v66, v67
	global_store_dwordx2 v[8:9], v[64:65], off offset:512
	v_pk_mul_f32 v[68:69], v[68:69], v[144:145] op_sel_hi:[1,0]
	v_pk_mul_f32 v[70:71], v[70:71], v[144:145] op_sel_hi:[1,0]
	v_pk_mul_f32 v[68:69], v[100:101], v[68:69]
	v_pk_mul_f32 v[70:71], v[102:103], v[70:71]
	v_pk_add_f32 v[116:117], v[116:117], 1.0 op_sel_hi:[1,0]
	v_pk_add_f32 v[118:119], v[118:119], 1.0 op_sel_hi:[1,0]
	v_pk_fma_f32 v[68:69], v[116:117], v[68:69], v[132:133]
	v_pk_fma_f32 v[70:71], v[118:119], v[70:71], v[134:135]
	v_cvt_pk_bf16_f32 v68, v68, v69
	v_cvt_pk_bf16_f32 v69, v70, v71
	global_store_dwordx2 v[8:9], v[68:69], off offset:1024
	v_pk_mul_f32 v[72:73], v[72:73], v[144:145] op_sel_hi:[1,0]
	v_pk_mul_f32 v[74:75], v[74:75], v[144:145] op_sel_hi:[1,0]
	v_pk_mul_f32 v[72:73], v[104:105], v[72:73]
	v_pk_mul_f32 v[74:75], v[106:107], v[74:75]
	v_pk_add_f32 v[120:121], v[120:121], 1.0 op_sel_hi:[1,0]
	v_pk_add_f32 v[122:123], v[122:123], 1.0 op_sel_hi:[1,0]
	v_pk_fma_f32 v[72:73], v[120:121], v[72:73], v[136:137]
	v_pk_fma_f32 v[74:75], v[122:123], v[74:75], v[138:139]
	v_cvt_pk_bf16_f32 v72, v72, v73
	v_cvt_pk_bf16_f32 v73, v74, v75
	global_store_dwordx2 v[8:9], v[72:73], off offset:1536
	v_mov_b32_e32 v0, v146
	v_lshl_add_u64 v[10:11], v[10:11], 0, s[14:15]
	v_cmp_lt_i32_e32 vcc, s56, v0
	s_or_b64 s[2:3], vcc, s[2:3]
	v_lshl_add_u64 v[8:9], v[8:9], 0, s[50:51]
	s_andn2_b64 exec, exec, s[2:3]
	s_cbranch_execnz .Lnorm_a_loop

; DI unsigned pk2(float lo, float hi) { f32x2_t v = {lo, hi}; bf16x2_t b = __builtin_convertvector(v, bf16x2_t); return __builtin_bit_cast(unsigned, b); }
; DI float sx(float v, int mask, int lane) { return __int_as_float(__builtin_amdgcn_ds_bpermute((lane ^ mask) << 2, __float_as_int(v))); }
; DI float wave_sum(float v, int lane) {
; #pragma unroll
;     for (int o = 1; o < 64; o <<= 1) v += sx(v, o, lane);
;     return v;
; }
; DI void phase_norm(const float* xin, const float* g, const float* shift, const float* scale, bf16* hout) {
;     ...
;         for (int j = 0; j < 4; ++j) { v[j] = xr[64 * j]; ss += (v[j].x * v[j].x + v[j].y * v[j].y) + (v[j].z * v[j].z + v[j].w * v[j].w); }
;         const float r = rsqrtf(wave_sum(ss, lane) * (1.f / DM) + EPS);
; #pragma unroll
;         for (int j = 0; j < 4; ++j) { const int col = 4 * lane + 256 * j;
;             const f32x4 gg = *(const f32x4*)(g + col), sc = *(const f32x4*)(scale + b * 6144 + col), sh = *(const f32x4*)(shift + b * 6144 + col);
;             const f32x4 y = (v[j] * r) * gg * (sc + 1.f) + sh;
;             u32x2 w; w.x = pk2(y.x, y.y); w.y = pk2(y.z, y.w);
;             *(u32x2*)(hout + (size_t)row * DM + col) = w; }
.Lnorm_b_body:
	v_mov_b32_e32 v60, v76
	v_mov_b32_e32 v61, v77
	v_mov_b32_e32 v62, v78
	v_mov_b32_e32 v63, v79
	v_mov_b32_e32 v64, v80
	v_mov_b32_e32 v65, v81
	v_mov_b32_e32 v66, v82
	v_mov_b32_e32 v67, v83
	v_mov_b32_e32 v68, v84
	v_mov_b32_e32 v69, v85
	v_mov_b32_e32 v70, v86
	v_mov_b32_e32 v71, v87
	v_mov_b32_e32 v72, v88
	v_mov_b32_e32 v73, v89
	v_mov_b32_e32 v74, v90
	v_mov_b32_e32 v75, v91
	v_ashrrev_i32_e32 v140, 11, v16
	v_mul_i32_i24_e32 v140, 0x1800, v140
	v_ashrrev_i32_e32 v141, 31, v140
	v_lshlrev_b64 v[140:141], 2, v[140:141]
	v_lshl_add_u64 v[150:151], v[20:21], 0, v[140:141]
	v_lshl_add_u64 v[152:153], v[22:23], 0, v[140:141]
	global_load_dwordx4 v[92:95], v[18:19], off
	global_load_dwordx4 v[96:99], v[18:19], off offset:1024
	global_load_dwordx4 v[100:103], v[18:19], off offset:2048
	global_load_dwordx4 v[104:107], v[18:19], off offset:3072
	global_load_dwordx4 v[108:111], v[150:151], off
	global_load_dwordx4 v[112:115], v[150:151], off offset:1024
	global_load_dwordx4 v[116:119], v[150:151], off offset:2048
	global_load_dwordx4 v[120:123], v[150:151], off offset:3072
	global_load_dwordx4 v[124:127], v[152:153], off
	global_load_dwordx4 v[128:131], v[152:153], off offset:1024
	global_load_dwordx4 v[132:135], v[152:153], off offset:2048
	global_load_dwordx4 v[136:139], v[152:153], off offset:3072
	v_add_u32_e32 v146, s84, v16
	v_lshl_add_u64 v[148:149], v[26:27], 0, s[8:9]
	v_cmp_lt_i32_e32 vcc, s56, v146
	s_nop 1
	v_cndmask_b32_e32 v148, v148, v26, vcc
	v_cndmask_b32_e32 v149, v149, v27, vcc
	global_load_dwordx4 v[76:79], v[148:149], off offset:-3072
	global_load_dwordx4 v[80:83], v[148:149], off offset:-2048
	global_load_dwordx4 v[84:87], v[148:149], off offset:-1024
	global_load_dwordx4 v[88:91], v[148:149], off
	v_mul_f32_e32 v154, v60, v60
	v_fmac_f32_e32 v154, v61, v61
	v_mul_f32_e32 v155, v62, v62
	v_fmac_f32_e32 v155, v63, v63
	v_add_f32_e32 v154, v154, v155
	v_mov_b32_e32 v142, v154
	v_mul_f32_e32 v154, v64, v64
	v_fmac_f32_e32 v154, v65, v65
	v_mul_f32_e32 v155, v66, v66
	v_fmac_f32_e32 v155, v67, v67
	v_add_f32_e32 v154, v154, v155
	v_add_f32_e32 v142, v142, v154
	v_mul_f32_e32 v154, v68, v68
	v_fmac_f32_e32 v154, v69, v69
	v_mul_f32_e32 v155, v70, v70
	v_fmac_f32_e32 v155, v71, v71
	v_add_f32_e32 v154, v154, v155
	v_add_f32_e32 v142, v142, v154
	v_mul_f32_e32 v154, v72, v72
	v_fmac_f32_e32 v154, v73, v73
	v_mul_f32_e32 v155, v74, v74
	v_fmac_f32_e32 v155, v75, v75
	v_add_f32_e32 v154, v154, v155
	v_add_f32_e32 v142, v142, v154
	s_nop 1
	v_add_f32_dpp v142, v142, v142 quad_perm:[1,0,3,2] row_mask:0xf bank_mask:0xf
	s_nop 1
	v_add_f32_dpp v142, v142, v142 quad_perm:[2,3,0,1] row_mask:0xf bank_mask:0xf
	s_nop 1
	v_add_f32_dpp v142, v142, v142 row_half_mirror row_mask:0xf bank_mask:0xf
	s_nop 1
	v_add_f32_dpp v142, v142, v142 row_mirror row_mask:0xf bank_mask:0xf
	ds_bpermute_b32 v154, v37, v142
	s_waitcnt lgkmcnt(0)
	v_add_f32_e32 v142, v142, v154
	ds_bpermute_b32 v154, v38, v142
	s_waitcnt lgkmcnt(0)
	v_add_f32_e32 v142, v142, v154
	v_fmamk_f32 v142, v142, 0x3a800000, v198
	v_mul_f32_e32 v154, 0x4b800000, v142
	v_cmp_gt_f32_e32 vcc, s67, v142
	s_nop 1
	v_cndmask_b32_e32 v142, v142, v154, vcc
	v_rsq_f32_e32 v142, v142
	s_nop 0
	v_mul_f32_e32 v154, 0x45800000, v142
	v_cndmask_b32_e32 v144, v142, v154, vcc
	s_waitcnt vmcnt(4)
	v_pk_mul_f32 v[60:61], v[60:61], v[144:145] op_sel_hi:[1,0]
	v_pk_mul_f32 v[62:63], v[62:63], v[144:145] op_sel_hi:[1,0]
	v_pk_mul_f32 v[60:61], v[92:93], v[60:61]
	v_pk_mul_f32 v[62:63], v[94:95], v[62:63]
	v_pk_add_f32 v[108:109], v[108:109], 1.0 op_sel_hi:[1,0]
	v_pk_add_f32 v[110:111], v[110:111], 1.0 op_sel_hi:[1,0]
	v_pk_fma_f32 v[60:61], v[108:109], v[60:61], v[124:125]
	v_pk_fma_f32 v[62:63], v[110:111], v[62:63], v[126:127]
	v_cvt_pk_bf16_f32 v60, v60, v61
	v_cvt_pk_bf16_f32 v61, v62, v63
	global_store_dwordx2 v[24:25], v[60:61], off
	v_pk_mul_f32 v[64:65], v[64:65], v[144:145] op_sel_hi:[1,0]
	v_pk_mul_f32 v[66:67], v[66:67], v[144:145] op_sel_hi:[1,0]
	v_pk_mul_f32 v[64:65], v[96:97], v[64:65]
	v_pk_mul_f32 v[66:67], v[98:99], v[66:67]
	v_pk_add_f32 v[112:113], v[112:113], 1.0 op_sel_hi:[1,0]
	v_pk_add_f32 v[114:115], v[114:115], 1.0 op_sel_hi:[1,0]
	v_pk_fma_f32 v[64:65], v[112:113], v[64:65], v[128:129]
	v_pk_fma_f32 v[66:67], v[114:115], v[66:67], v[130:131]
	v_cvt_pk_bf16_f32 v64, v64, v65
	v_cvt_pk_bf16_f32 v65, v66, v67
	global_store_dwordx2 v[24:25], v[64:65], off offset:512
	v_pk_mul_f32 v[68:69], v[68:69], v[144:145] op_sel_hi:[1,0]
	v_pk_mul_f32 v[70:71], v[70:71], v[144:145] op_sel_hi:[1,0]
	v_pk_mul_f32 v[68:69], v[100:101], v[68:69]
	v_pk_mul_f32 v[70:71], v[102:103], v[70:71]
	v_pk_add_f32 v[116:117], v[116:117], 1.0 op_sel_hi:[1,0]
	v_pk_add_f32 v[118:119], v[118:119], 1.0 op_sel_hi:[1,0]
	v_pk_fma_f32 v[68:69], v[116:117], v[68:69], v[132:133]
	v_pk_fma_f32 v[70:71], v[118:119], v[70:71], v[134:135]
	v_cvt_pk_bf16_f32 v68, v68, v69
	v_cvt_pk_bf16_f32 v69, v70, v71
	global_store_dwordx2 v[24:25], v[68:69], off offset:1024
	v_pk_mul_f32 v[72:73], v[72:73], v[144:145] op_sel_hi:[1,0]
	v_pk_mul_f32 v[74:75], v[74:75], v[144:145] op_sel_hi:[1,0]
	v_pk_mul_f32 v[72:73], v[104:105], v[72:73]
	v_pk_mul_f32 v[74:75], v[106:107], v[74:75]
	v_pk_add_f32 v[120:121], v[120:121], 1.0 op_sel_hi:[1,0]
	v_pk_add_f32 v[122:123], v[122:123], 1.0 op_sel_hi:[1,0]
	v_pk_fma_f32 v[72:73], v[120:121], v[72:73], v[136:137]
	v_pk_fma_f32 v[74:75], v[122:123], v[74:75], v[138:139]
	v_cvt_pk_bf16_f32 v72, v72, v73
	v_cvt_pk_bf16_f32 v73, v74, v75
	global_store_dwordx2 v[24:25], v[72:73], off offset:1536
	v_mov_b32_e32 v16, v146
	v_lshl_add_u64 v[26:27], v[26:27], 0, s[8:9]
	v_cmp_lt_i32_e32 vcc, s56, v16
	s_or_b64 s[2:3], vcc, s[2:3]
	v_lshl_add_u64 v[24:25], v[24:25], 0, s[50:51]
	s_andn2_b64 exec, exec, s[2:3]
	s_cbranch_execnz .Lnorm_b_loop
